# ctx part2: normalisation loads requested before the slot poll (one round trip instead of two)
# baseline (speedup 1.0000x reference)
.LBB0_973:
.LBB0_974:
	v_readlane_b32 s4, v255, 0
	v_readlane_b32 s5, v255, 1
	s_and_b64 vcc, exec, s[4:5]
	v_readlane_b32 s46, v254, 17
	s_mov_b32 s73, 0xf700000
	s_mov_b32 s72, 0x24000
	s_movk_i32 s63, 0x9ff
	s_mov_b64 s[70:71], 0x800
	v_readlane_b32 s47, v254, 18
	s_cbranch_vccnz .LBB0_982
	v_mov_b32_e32 v0, v244
	s_lshl_b32 s4, s94, 1
	s_andn2_b32 s4, s4, 31
	v_ashrrev_i32_e32 v2, 4, v0
	v_add_u32_e32 v2, s4, v2
	v_ashrrev_i32_e32 v3, 31, v2
	v_and_b32_e32 v6, 15, v0
	v_lshlrev_b64 v[24:25], 6, v[2:3]
	v_lshl_add_u64 v[24:25], s[22:23], 0, v[24:25]
	v_lshlrev_b32_e32 v0, 2, v6
	v_lshl_add_u64 v[24:25], v[24:25], 0, v[0:1]
	s_waitcnt lgkmcnt(0)
	s_add_u32 s4, s53, s12
	s_addc_u32 s5, s61, 0
	s_lshl_b32 s6, s13, 2
	s_add_u32 s4, s4, s6
	s_addc_u32 s5, s5, 0
	s_lshl_b32 s6, s94, 6
	s_and_b32 s6, s6, 0x3c0
	v_lshlrev_b64 v[4:5], 12, v[2:3]
	v_lshl_add_u64 v[4:5], s[20:21], 0, v[4:5]
	s_lshl_b32 s80, s6, 2
	v_lshl_add_u64 v[4:5], v[4:5], 0, s[80:81]
	v_lshlrev_b32_e32 v0, 4, v6
	v_lshl_or_b32 v6, v6, 2, s6
	v_lshl_add_u64 v[4:5], v[4:5], 0, v[0:1]
	v_lshlrev_b32_e32 v0, 2, v6
	v_lshl_add_u64 v[20:21], s[4:5], 0, v[0:1]
	s_mov_b32 s4, 0x13000
	v_add_co_u32_e32 v16, vcc, s4, v20
	global_load_dwordx4 v[8:11], v0, s[14:15]
	s_nop 0
	v_addc_co_u32_e32 v17, vcc, 0, v21, vcc
	global_load_dwordx4 v[12:15], v[4:5], off
	s_nop 0
	global_load_dwordx4 v[16:19], v[16:17], off
	v_add_co_u32_e32 v4, vcc, s45, v20
	s_nop 1
	v_addc_co_u32_e32 v5, vcc, 0, v21, vcc
	global_load_dwordx4 v[20:23], v[4:5], off
	s_memrealtime s[4:5]
	s_branch .LBB0_978

.LBB0_978:
	global_load_dword v7, v[24:25], off sc1
	s_waitcnt vmcnt(0)
	v_cmp_eq_u32_e32 vcc, 0, v7
	s_cbranch_vccz .LBB0_976
	s_memrealtime s[6:7]
	s_waitcnt lgkmcnt(0)
	s_sub_u32 s6, s6, s4
	s_subb_u32 s7, s7, s5
	v_cmp_lt_u64_e32 vcc, s[6:7], v[252:253]
	s_mov_b64 s[6:7], -1
	s_cbranch_vccz .LBB0_977
	s_sleep 1
	s_mov_b64 s[6:7], 0
	s_branch .LBB0_977
.LBB0_981:
	s_waitcnt lgkmcnt(0)
	v_mov_b32_e32 v0, v7
	s_nop 1
	v_mov_b32_dpp v0, v0 quad_perm:[1,0,3,2] row_mask:0xf bank_mask:0xf
	v_add_f32_e32 v0, v0, v7
	v_mov_b32_e32 v4, v0
	v_add_u32_e32 v2, 0x4000, v2
	v_ashrrev_i32_e32 v3, 31, v2
	v_mov_b32_dpp v4, v4 quad_perm:[2,3,0,1] row_mask:0xf bank_mask:0xf
	v_add_f32_e32 v0, v0, v4
	v_mov_b32_e32 v4, v0
	v_lshlrev_b64 v[2:3], 11, v[2:3]
	v_lshl_add_u64 v[2:3], s[92:93], 0, v[2:3]
	v_mov_b32_dpp v4, v4 row_half_mirror row_mask:0xf bank_mask:0xf
	v_add_f32_e32 v0, v0, v4
	v_mov_b32_e32 v4, v0
	s_mov_b64 s[4:5], -1
	v_writelane_b32 v254, s4, 37
	v_mov_b32_dpp v4, v4 row_mirror row_mask:0xf bank_mask:0xf
	v_add_f32_e32 v0, v0, v4
	v_fmamk_f32 v0, v0, 0x3a800000, v218
	v_mul_f32_e32 v4, 0x4b800000, v0
	v_cmp_gt_f32_e32 vcc, s86, v0
	v_writelane_b32 v254, s5, 38
	s_nop 0
	v_cndmask_b32_e32 v0, v0, v4, vcc
	v_rsq_f32_e32 v4, v0
	v_lshlrev_b32_e32 v0, 1, v6
	v_lshl_add_u64 v[2:3], v[2:3], 0, v[0:1]
	v_mul_f32_e32 v0, 0x45800000, v4
	v_cndmask_b32_e32 v0, v4, v0, vcc
	s_waitcnt vmcnt(2)
	v_pk_mul_f32 v[6:7], v[14:15], v[0:1] op_sel_hi:[1,0]
	s_waitcnt vmcnt(1)
	v_pk_add_f32 v[14:15], v[16:17], 1.0 op_sel_hi:[1,0]
	v_pk_mul_f32 v[4:5], v[12:13], v[0:1] op_sel_hi:[1,0]
	v_pk_add_f32 v[12:13], v[18:19], 1.0 op_sel_hi:[1,0]
	v_pk_mul_f32 v[8:9], v[8:9], v[14:15]
	v_pk_mul_f32 v[10:11], v[10:11], v[12:13]
	s_waitcnt vmcnt(0)
	v_pk_fma_f32 v[4:5], v[8:9], v[4:5], v[20:21]
	v_pk_fma_f32 v[6:7], v[10:11], v[6:7], v[22:23]
	v_cvt_pk_bf16_f32 v4, v4, v5
	s_nop 0
	v_cvt_pk_bf16_f32 v5, v6, v7
	global_store_dwordx2 v[2:3], v[4:5], off
	s_barrier
